# G1 tiles: row-sum loads hoisted to the tile-loop header; epilogue vmcnt(0) kept only for gate-bias tiles; counted exit wait
# baseline (speedup 1.0000x reference)
; template <class Epi, class Sched, bool ALIGN_EPI = false, bool SP2 = false>
; __device__ __forceinline__ void gemm_phase(PG8_LAS unsigned char* lds, const Gemm g, const Sched& S, const Epi& E) {
;     ...
;         for (int a = 0; a < 2; ++a)
; #pragma unroll
;             for (int b = 0; b < 2; ++b)
; #pragma unroll
;                 for (int m = 0; m < 4; ++m)
; #pragma unroll
;                     for (int n = 0; n < 2; ++n) acc[a][b][m][n] = (f32x4){0.f, 0.f, 0.f, 0.f};
;         cur = nxt; cA = nA; cB = nB; ++ui;
;     __device__ __forceinline__ void operator()(const f32x4 (&acc)[2][2][4][2], const Unit& u, int wr, int wc, int fr, int fq) const {
;     ...
;             for (int m = 0; m < 4; ++m) rsv[ai][m] = ss[row0 + ai * 128 + m * 16];
.LBB0_217:
	s_ashr_i32 s15, s14, 31
	s_lshl_b64 s[16:17], s[14:15], 19
	s_add_u32 s16, s30, s16
	s_addc_u32 s17, s31, s17
	s_and_b64 s[18:19], s[4:5], exec
	s_cselect_b32 s15, s17, s7
	s_cselect_b32 s29, s16, s6
	s_ashr_i32 s13, s12, 31
	s_lshl_b64 s[18:19], s[12:13], 19
	v_readlane_b32 s13, v255, 37
	s_add_u32 s18, s13, s18
	v_readlane_b32 s13, v255, 38
	s_addc_u32 s19, s13, s19
	s_and_b64 s[22:23], s[4:5], exec
	s_cselect_b32 s13, s19, s1
	s_cselect_b32 s63, s18, s0
	s_add_u32 s6, s6, 0x40080
	s_addc_u32 s7, s7, 0
	s_add_u32 s22, s0, 0x100
	v_mov_b32_e32 v20, 0
	s_addc_u32 s23, s1, 0
	s_mov_b32 s35, -2
	v_mov_b32_e32 v21, v20
	v_mov_b32_e32 v22, v20
	v_mov_b32_e32 v23, v20
	v_mov_b32_e32 v24, v20
	v_mov_b32_e32 v25, v20
	v_mov_b32_e32 v26, v20
	v_mov_b32_e32 v27, v20
	v_mov_b32_e32 v36, v20
	v_mov_b32_e32 v37, v20
	v_mov_b32_e32 v38, v20
	v_mov_b32_e32 v39, v20
	v_mov_b32_e32 v40, v20
	v_mov_b32_e32 v41, v20
	v_mov_b32_e32 v42, v20
	v_mov_b32_e32 v43, v20
	v_mov_b32_e32 v52, v20
	v_mov_b32_e32 v53, v20
	v_mov_b32_e32 v54, v20
	v_mov_b32_e32 v55, v20
	v_mov_b32_e32 v56, v20
	v_mov_b32_e32 v57, v20
	v_mov_b32_e32 v58, v20
	v_mov_b32_e32 v59, v20
	v_mov_b32_e32 v68, v20
	v_mov_b32_e32 v69, v20
	v_mov_b32_e32 v70, v20
	v_mov_b32_e32 v71, v20
	v_mov_b32_e32 v72, v20
	v_mov_b32_e32 v73, v20
	v_mov_b32_e32 v74, v20
	v_mov_b32_e32 v75, v20
	v_mov_b32_e32 v28, v20
	v_mov_b32_e32 v29, v20
	v_mov_b32_e32 v30, v20
	v_mov_b32_e32 v31, v20
	v_mov_b32_e32 v32, v20
	v_mov_b32_e32 v33, v20
	v_mov_b32_e32 v34, v20
	v_mov_b32_e32 v35, v20
	v_mov_b32_e32 v44, v20
	v_mov_b32_e32 v45, v20
	v_mov_b32_e32 v46, v20
	v_mov_b32_e32 v47, v20
	v_mov_b32_e32 v48, v20
	v_mov_b32_e32 v49, v20
	v_mov_b32_e32 v50, v20
	v_mov_b32_e32 v51, v20
	v_mov_b32_e32 v60, v20
	v_mov_b32_e32 v61, v20
	v_mov_b32_e32 v62, v20
	v_mov_b32_e32 v63, v20
	v_mov_b32_e32 v64, v20
	v_mov_b32_e32 v65, v20
	v_mov_b32_e32 v66, v20
	v_mov_b32_e32 v67, v20
	v_mov_b32_e32 v76, v20
	v_mov_b32_e32 v77, v20
	v_mov_b32_e32 v78, v20
	v_mov_b32_e32 v79, v20
	v_mov_b32_e32 v80, v20
	v_mov_b32_e32 v81, v20
	v_mov_b32_e32 v82, v20
	v_mov_b32_e32 v83, v20
	v_mov_b32_e32 v96, v20
	v_mov_b32_e32 v97, v20
	v_mov_b32_e32 v98, v20
	v_mov_b32_e32 v99, v20
	v_mov_b32_e32 v104, v20
	v_mov_b32_e32 v105, v20
	v_mov_b32_e32 v106, v20
	v_mov_b32_e32 v107, v20
	v_mov_b32_e32 v116, v20
	v_mov_b32_e32 v117, v20
	v_mov_b32_e32 v118, v20
	v_mov_b32_e32 v119, v20
	v_mov_b32_e32 v120, v20
	v_mov_b32_e32 v121, v20
	v_mov_b32_e32 v122, v20
	v_mov_b32_e32 v123, v20
	v_mov_b32_e32 v132, v20
	v_mov_b32_e32 v133, v20
	v_mov_b32_e32 v134, v20
	v_mov_b32_e32 v135, v20
	v_mov_b32_e32 v136, v20
	v_mov_b32_e32 v137, v20
	v_mov_b32_e32 v138, v20
	v_mov_b32_e32 v139, v20
	v_mov_b32_e32 v148, v20
	v_mov_b32_e32 v149, v20
	v_mov_b32_e32 v150, v20
	v_mov_b32_e32 v151, v20
	v_mov_b32_e32 v152, v20
	v_mov_b32_e32 v153, v20
	v_mov_b32_e32 v154, v20
	v_mov_b32_e32 v155, v20
	v_mov_b32_e32 v108, v20
	v_mov_b32_e32 v109, v20
	v_mov_b32_e32 v110, v20
	v_mov_b32_e32 v111, v20
	v_mov_b32_e32 v112, v20
	v_mov_b32_e32 v113, v20
	v_mov_b32_e32 v114, v20
	v_mov_b32_e32 v115, v20
	v_mov_b32_e32 v124, v20
	v_mov_b32_e32 v125, v20
	v_mov_b32_e32 v126, v20
	v_mov_b32_e32 v127, v20
	v_mov_b32_e32 v128, v20
	v_mov_b32_e32 v129, v20
	v_mov_b32_e32 v130, v20
	v_mov_b32_e32 v131, v20
	v_mov_b32_e32 v140, v20
	v_mov_b32_e32 v141, v20
	v_mov_b32_e32 v142, v20
	v_mov_b32_e32 v143, v20
	v_mov_b32_e32 v144, v20
	v_mov_b32_e32 v145, v20
	v_mov_b32_e32 v146, v20
	v_mov_b32_e32 v147, v20
	v_mov_b32_e32 v156, v20
	v_mov_b32_e32 v157, v20
	v_mov_b32_e32 v158, v20
	v_mov_b32_e32 v159, v20
	v_mov_b32_e32 v160, v20
	v_mov_b32_e32 v161, v20
	v_mov_b32_e32 v162, v20
	v_mov_b32_e32 v163, v20
	v_lshl_add_u32 v12, s62, 8, v180
	v_mov_b32_e32 v13, 0
	v_lshl_add_u64 v[14:15], v[12:13], 2, s[38:39]
	global_load_dword v4, v[14:15], off
	global_load_dword v5, v[14:15], off offset:64
	global_load_dword v6, v[14:15], off offset:128
	global_load_dword v7, v[14:15], off offset:192
	global_load_dword v8, v[14:15], off offset:512
	global_load_dword v9, v[14:15], off offset:576
	global_load_dword v10, v[14:15], off offset:640
	global_load_dword v11, v[14:15], off offset:704

; __device__ __forceinline__ float sigm(float x) { return __builtin_amdgcn_rcpf(1.f + __builtin_amdgcn_exp2f(-LOG2E * x)); }
;     __device__ __forceinline__ void operator()(const f32x4 (&acc)[2][2][4][2], const Unit& u, int wr, int wc, int fr, int fq) const {
;         const int row0 = u.pm * 256 + wr * 64 + fr, col0 = (u.pn + pn0) * 256 + wc * 32 + 8 * fq; const bool gate = u.pn + pn0 >= 5;
;         f32x4 bv[2][2];
; #pragma unroll
;         for (int bj = 0; bj < 2; ++bj)
; #pragma unroll
;             for (int n = 0; n < 2; ++n) bv[bj][n] = gate ? *(const f32x4*)(bgate + (col0 - ZG) + bj * 128 + 4 * n) : (f32x4){0.f, 0.f, 0.f, 0.f};
;         float rsv[2][4];
; #pragma unroll
;         for (int ai = 0; ai < 2; ++ai)
; #pragma unroll
;             for (int m = 0; m < 4; ++m) rsv[ai][m] = ss[row0 + ai * 128 + m * 16];
;         __builtin_amdgcn_sched_barrier(0);
; #pragma unroll
;         for (int ai = 0; ai < 2; ++ai)
; #pragma unroll
;             for (int m = 0; m < 4; ++m) { const int row = row0 + ai * 128 + m * 16; const float rs = rsqrtf(rsv[ai][m] * (1.f / DM) + EPS); bf16_t* rowp = Z + (size_t)row * INC + col0;
; #pragma unroll
;                 for (int bj = 0; bj < 2; ++bj) { f32x4 v0 = acc[ai][bj][m][0] * rs + bv[bj][0], v1 = acc[ai][bj][m][1] * rs + bv[bj][1];
;                     if (gate) { v0 = (f32x4){sigm(v0[0]), sigm(v0[1]), sigm(v0[2]), sigm(v0[3])}; v1 = (f32x4){sigm(v1[0]), sigm(v1[1]), sigm(v1[2]), sigm(v1[3])}; }
.LBB0_229:
	v_lshl_add_u32 v174, s62, 8, v180
	v_ashrrev_i32_e32 v175, 31, v174
	v_lshl_add_u64 v[176:177], v[174:175], 2, s[38:39]
	v_mov_b32_e32 v173, v4
	v_mov_b32_e32 v195, v5
	v_mov_b32_e32 v194, v6
	v_mov_b32_e32 v193, v7
	v_mov_b32_e32 v192, v8
	v_mov_b32_e32 v191, v9
	v_mov_b32_e32 v190, v10
	v_mov_b32_e32 v175, v11
	s_and_b64 vcc, exec, s[6:7]
	s_cbranch_vccnz .Lepi_g1_nowait
	s_waitcnt vmcnt(0)
.Lepi_g1_nowait:
	v_fmamk_f32 v173, v173, 0x3a800000, v185
	v_mul_f32_e32 v176, 0x4b800000, v173
	v_cmp_gt_f32_e32 vcc, s86, v173
	s_nop 1
	v_cndmask_b32_e32 v173, v173, v176, vcc
	v_rsq_f32_e32 v173, v173
	s_nop 0
	v_mul_f32_e32 v176, 0x45800000, v173
	v_cndmask_b32_e32 v176, v173, v176, vcc
	v_pk_fma_f32 v[162:163], v[162:163], v[176:177], v[102:103] op_sel_hi:[1,0,1]
	v_pk_fma_f32 v[160:161], v[160:161], v[176:177], v[100:101] op_sel_hi:[1,0,1]
	v_pk_fma_f32 v[158:159], v[158:159], v[176:177], v[94:95] op_sel_hi:[1,0,1]
	s_and_b64 vcc, exec, s[6:7]
	v_pk_fma_f32 v[178:179], v[156:157], v[176:177], v[92:93] op_sel_hi:[1,0,1]
	s_cbranch_vccnz .LBB0_231
	v_mul_f32_e32 v156, 0xbfb8aa3b, v160
	v_exp_f32_e32 v156, v156
	v_mul_f32_e32 v157, 0xbfb8aa3b, v161
	v_exp_f32_e32 v157, v157
	v_mul_f32_e32 v161, 0xbfb8aa3b, v163
	v_add_f32_e32 v156, 1.0, v156
	v_rcp_f32_e32 v160, v156
	v_mul_f32_e32 v156, 0xbfb8aa3b, v162
	v_add_f32_e32 v157, 1.0, v157
	v_exp_f32_e32 v156, v156
	v_exp_f32_e32 v163, v161
	v_rcp_f32_e32 v161, v157
	v_mul_f32_e32 v157, 0xbfb8aa3b, v178
	v_exp_f32_e32 v157, v157
	v_add_f32_e32 v156, 1.0, v156
	v_rcp_f32_e32 v162, v156
	v_add_f32_e32 v156, 1.0, v163
	v_mul_f32_e32 v163, 0xbfb8aa3b, v179
	v_exp_f32_e32 v173, v163
	v_rcp_f32_e32 v163, v156
	v_add_f32_e32 v156, 1.0, v157
	v_mul_f32_e32 v157, 0xbfb8aa3b, v158
	v_exp_f32_e32 v157, v157
	v_mul_f32_e32 v158, 0xbfb8aa3b, v159
	v_exp_f32_e32 v159, v158
	v_rcp_f32_e32 v178, v156
	v_add_f32_e32 v156, 1.0, v173
	v_rcp_f32_e32 v179, v156
	v_add_f32_e32 v156, 1.0, v157
	v_rcp_f32_e32 v158, v156
	v_add_f32_e32 v156, 1.0, v159
	v_rcp_f32_e32 v159, v156

; #define PG8_WAIT_V(n) asm volatile("s_waitcnt vmcnt(" #n ")" ::: "memory")
; #define PG8_BAR __builtin_amdgcn_s_barrier()
; template <class Epi, class Sched, bool ALIGN_EPI = false, bool SP2 = false>
; __device__ __forceinline__ void gemm_phase(PG8_LAS unsigned char* lds, const Gemm g, const Sched& S, const Epi& E) {
;     ...
;     PG8_WAIT_V(0);
;     if constexpr (!ALIGN_EPI) { if (wr == 0) PG8_BAR; }
;     PG8_BAR;
.LBB0_264:
	s_waitcnt vmcnt(16)
	v_readlane_b32 s28, v255, 30
	v_readlane_b32 s29, v255, 31
	s_mov_b32 s35, 0x18000
	s_mov_b32 s72, 0xc000
	s_barrier
